# phase 1 tiles taken from per-XCD-group atomic queues (next index fetched during the k-loop) instead of a static stride
# baseline (speedup 1.0000x reference)
; __device__ __forceinline__ void phase1(const Params& p, unsigned char* smem) {
;     ...
;   const int xcd = blockIdx.x & 7, lw = blockIdx.x >> 3, LW = (gridDim.x - xcd + 7) >> 3;
;   for (int i = lw;; i += LW) {
;     int mt, nt; if (!tile_map(i, xcd, 129, 49, mt, nt)) break;
;     const int m0 = mt * 128;
;     const int n0 = nt < 24 ? nt * 128 : (nt < 48 ? 4096 + (nt - 24) * 128 : 8192);
;     f32x16 acc[2][2]; zero_acc(acc);
;     gemm_kloop(acc, [&](int m) { int mm = m < NTOK ? m : NTOK - 1; return hn + (size_t)mm * DM; }, [](int k0) { return (size_t)k0; }, wtin, m0, n0, smem);
.LBB0_83:
	s_or_b64 exec, exec, s[4:5]
	s_add_u32 s12, s48, 0x2010000
	s_addc_u32 s13, s49, 0
	s_add_u32 s14, s50, 0x2010000
	s_addc_u32 s15, s51, 0
	s_add_u32 s16, s50, 0x4050000
	s_addc_u32 s17, s51, 0
	s_add_u32 s18, s50, 0x6090000
	s_addc_u32 s19, s51, 0
	s_and_b32 s73, s89, 7
	s_xor_b32 s2, s73, 7
	s_add_i32 s2, s3, s2
	s_lshr_b32 s65, s2, 3
	s_sub_i32 s2, 0x88, s73
	s_lshr_b32 s33, s89, 3
	s_lshr_b32 s2, s2, 3
	s_add_u32 s20, s48, 0x80
	s_addc_u32 s21, s49, 0
	s_add_u32 s22, s48, 0x10080
	s_load_dwordx4 s[8:11], s[0:1], 0x50
	s_addc_u32 s23, s49, 0
	s_add_u32 s24, s48, 0x20080
	s_addc_u32 s25, s49, 0
	s_add_u32 s26, s48, 0x30080
	s_addc_u32 s27, s49, 0
	v_mov_b32_e32 v97, 0
	s_mov_b32 s37, 0x10000
	s_mov_b32 s44, 0x20000
	s_mov_b32 s45, 0x30000
	s_movk_i32 s46, 0x90
	s_mov_b32 s47, 0xfffffc0
	s_mov_b64 s[28:29], 0x3fff
	s_mov_b64 s[30:31], 0x3fdf
	s_mov_b64 s[34:35], 0x3fbf
	s_movk_i32 s52, 0x210
	s_movk_i32 s53, 0x2010
	s_movk_i32 s54, 0x2008
	s_movk_i32 s55, 0x4020
	s_mov_b32 s56, 0x7fc01ff1
	s_mov_b32 s57, 0x41a00000
	s_mov_b32 s58, 0x3f2aaaab
	v_mov_b32_e32 v110, 0x3ecc95a3
	s_mov_b32 s59, 0x3f317218
	s_mov_b32 s60, 0x7f800000
	s_mov_b32 s61, 0x33800000
	s_movk_i32 s62, 0xdff0
	s_movk_i32 s63, 0x81
	s_movk_i32 s64, 0x300
	s_movk_i32 s66, 0x4080
	s_mov_b32 s36, 0x3e38aa3b
	v_mov_b32_e32 v111, 0x3fff
	v_mov_b32_e32 v112, 0x3fdf
	v_mov_b32_e32 v113, 0x3fbf
	v_mov_b32_e32 v98, 0x3f317218
	v_mov_b32_e32 v114, 0x7f800000
	v_mov_b32_e32 v115, 0x7fc00000
	v_mov_b32_e32 v116, 0xff800000
	s_mov_b32 s67, s33
	s_barrier
	s_waitcnt lgkmcnt(0)
	s_load_dwordx8 s[76:83], s[10:11], 0x0
	s_load_dwordx8 s[92:99], s[8:9], 0x0
	s_waitcnt lgkmcnt(0)
	s_lshl_b32 s84, s73, 2
	s_add_u32 s86, s50, 0xf223f00
	s_addc_u32 s87, s51, 0
	s_add_u32 s86, s86, s84
	s_addc_u32 s87, s87, 0
	v_cmp_eq_u32_e32 vcc, 0, v218
	s_and_saveexec_b64 s[84:85], vcc
	s_cbranch_execz .Ltq1_init_skip
	v_mov_b32_e32 v246, 1
	global_atomic_add v246, v97, v246, s[86:87] sc0
	s_waitcnt vmcnt(0)
	ds_write_b32 v97, v246
	s_waitcnt lgkmcnt(0)
.Ltq1_init_skip:
	s_or_b64 exec, exec, s[84:85]
	s_barrier
	ds_read_b32 v221, v97
	s_waitcnt lgkmcnt(0)
	v_readfirstlane_b32 s67, v221
	s_nop 0
	s_branch .LBB0_87

; __device__ __forceinline__ void phase1(const Params& p, unsigned char* smem) {
;     ...
;   for (int i = lw;; i += LW) {
;     int mt, nt; if (!tile_map(i, xcd, 129, 49, mt, nt)) break;
.LBB0_85:
	ds_read_b32 v221, v97
	s_waitcnt lgkmcnt(0)
	v_readfirstlane_b32 s67, v221
	s_nop 0
	s_mov_b64 s[4:5], 0
	s_waitcnt lgkmcnt(0)

; __device__ __forceinline__ bool tile_map(int i, int xcd, int MT, int NT, int& mt, int& nt) {
;   int cm = (MT - xcd + 7) >> 3;
;   int ag = i / (8 * NT);
;   if (ag * 8 >= cm) return false;
;   int gs = cm - ag * 8; if (gs > 8) gs = 8;
;   int j = i - ag * 8 * NT;
;   if (j >= gs * NT) return false;
;   int al = j % gs; nt = j / gs;
;   mt = xcd + 8 * (8 * ag + al);
;   return true;
; }
; __device__ __forceinline__ void phase1(const Params& p, unsigned char* smem) {
;     ...
;     int mt, nt; if (!tile_map(i, xcd, 129, 49, mt, nt)) break;
;     const int m0 = mt * 128;
;     const int n0 = nt < 24 ? nt * 128 : (nt < 48 ? 4096 + (nt - 24) * 128 : 8192);
.Ltm1_extra:
	s_sub_i32 s38, s67, 0x310
	s_lshl_b32 s38, s38, 3
	s_add_i32 s68, s38, s73
	s_cmp_gt_u32 s68, 48
	s_cbranch_scc1 .LBB0_90
	s_movk_i32 s69, 0x80

; __device__ __forceinline__ void lds_barrier() { asm volatile("s_waitcnt lgkmcnt(0)\n\ts_barrier" ::: "memory"); }
; template <class ARowF, class KOffF>
; __device__ __forceinline__ void gemm_kloop(f32x16 (&acc)[2][2], ARowF arow, KOffF koff, const u16* __restrict__ Bt, int m0, int n0, unsigned char* smem) {
;     ...
;   const u16* pa0 = arow(m0 + lr) + lc * 8; const u16* pa1 = arow(m0 + lr + 32) + lc * 8;
;   const u16* pa2 = arow(m0 + lr + 64) + lc * 8; const u16* pa3 = arow(m0 + lr + 96) + lc * 8;
;   const u16* pb0 = Bt + (size_t)(n0 + lr) * 1024 + lc * 8;
;   u32x4 ra0, ra1, ra2, ra3, rb0, rb1, rb2, rb3;
;   {
;     const size_t ko = koff(0);
;     ra0 = *(const u32x4*)(pa0 + ko); ra1 = *(const u32x4*)(pa1 + ko); ra2 = *(const u32x4*)(pa2 + ko); ra3 = *(const u32x4*)(pa3 + ko);
;     rb0 = *(const u32x4*)(pb0); rb1 = *(const u32x4*)(pb0 + 32 * 1024); rb2 = *(const u32x4*)(pb0 + 64 * 1024); rb3 = *(const u32x4*)(pb0 + 96 * 1024);
;   }
;   u16* wA0 = sA + lr * 72 + lc * 8; u16* wB0 = sB + lr * 72 + lc * 8;
;   *(u32x4*)(wA0) = ra0; *(u32x4*)(wA0 + 32 * 72) = ra1; *(u32x4*)(wA0 + 64 * 72) = ra2; *(u32x4*)(wA0 + 96 * 72) = ra3;
;   *(u32x4*)(wB0) = rb0; *(u32x4*)(wB0 + 32 * 72) = rb1; *(u32x4*)(wB0 + 64 * 72) = rb2; *(u32x4*)(wB0 + 96 * 72) = rb3;
;   lds_barrier();
; #pragma unroll 1
;   for (int kt = 0; kt < 16; ++kt) {
;     const int buf = kt & 1;
;     if (kt + 1 < 16) {
;       const size_t ko = koff((kt + 1) * 64); const int kb = (kt + 1) * 64;
;       ra0 = *(const u32x4*)(pa0 + ko); ra1 = *(const u32x4*)(pa1 + ko); ra2 = *(const u32x4*)(pa2 + ko); ra3 = *(const u32x4*)(pa3 + ko);
;       rb0 = *(const u32x4*)(pb0 + kb); rb1 = *(const u32x4*)(pb0 + 32 * 1024 + kb); rb2 = *(const u32x4*)(pb0 + 64 * 1024 + kb); rb3 = *(const u32x4*)(pb0 + 96 * 1024 + kb);
.LBB0_95:
	v_cmp_eq_u32_e32 vcc, 0, v218
	s_and_saveexec_b64 s[84:85], vcc
	s_cbranch_execz .Ltq1_a_skip
	v_mov_b32_e32 v246, 1
	global_atomic_add v246, v97, v246, s[86:87] sc0
.Ltq1_a_skip:
	s_or_b64 exec, exec, s[84:85]
	v_mov_b32_e32 v1, v218
	s_lshl_b32 s70, s69, 7
	s_mov_b32 s40, 0
	v_ashrrev_i32_e32 v16, 3, v1
	v_add_u32_e32 v0, s70, v16
	v_lshlrev_b32_e32 v6, 4, v1
	v_and_b32_e32 v96, 0x70, v6
	v_min_i32_e32 v6, 0x3fff, v0
	v_ashrrev_i32_e32 v7, 31, v6
	v_lshlrev_b64 v[6:7], 11, v[6:7]
	v_min_i32_e32 v8, 0x3fdf, v0
	v_lshl_add_u64 v[6:7], s[48:49], 0, v[6:7]
	v_ashrrev_i32_e32 v9, 31, v8
	v_lshl_add_u64 v[6:7], v[6:7], 0, v[96:97]
	v_lshlrev_b64 v[8:9], 11, v[8:9]
	v_min_i32_e32 v10, 0x3fbf, v0
	v_lshl_add_u64 v[8:9], s[48:49], 0, v[8:9]
	v_ashrrev_i32_e32 v11, 31, v10
	v_add_co_u32_e32 v6, vcc, s37, v6
	v_min_i32_e32 v2, 0x401f, v0
	v_lshl_add_u64 v[8:9], v[8:9], 0, v[96:97]
	v_lshlrev_b64 v[10:11], 11, v[10:11]
	v_add_u32_e32 v12, s71, v16
	v_addc_co_u32_e32 v7, vcc, 0, v7, vcc
	v_ashrrev_i32_e32 v3, 31, v2
	v_lshl_add_u64 v[10:11], s[48:49], 0, v[10:11]
	v_ashrrev_i32_e32 v13, 31, v12
	v_add_co_u32_e32 v8, vcc, s44, v8
	v_lshlrev_b64 v[2:3], 11, v[2:3]
	v_lshl_add_u64 v[10:11], v[10:11], 0, v[96:97]
	v_lshlrev_b64 v[12:13], 11, v[12:13]
	v_addc_co_u32_e32 v9, vcc, 0, v9, vcc
	v_lshl_add_u64 v[4:5], s[48:49], 0, v[2:3]
	v_lshl_add_u64 v[14:15], s[12:13], 0, v[12:13]
	global_load_dwordx4 v[64:67], v[6:7], off
	global_load_dwordx4 v[72:75], v[8:9], off
	v_add_co_u32_e32 v6, vcc, s45, v10
	v_lshl_add_u64 v[4:5], v[4:5], 0, v[96:97]
	v_lshl_add_u64 v[14:15], v[14:15], 0, v[96:97]
	v_addc_co_u32_e32 v7, vcc, 0, v11, vcc
	global_load_dwordx4 v[68:71], v[4:5], off
	global_load_dwordx4 v[76:79], v[14:15], off
	v_add_co_u32_e32 v4, vcc, s44, v14
	v_or_b32_e32 v2, v2, v96
	s_nop 0
	v_addc_co_u32_e32 v5, vcc, 0, v15, vcc
	v_add_co_u32_e32 v8, vcc, s45, v14
	v_lshl_add_u64 v[100:101], s[20:21], 0, v[2:3]
	s_nop 0
	v_addc_co_u32_e32 v9, vcc, 0, v15, vcc
	global_load_dwordx4 v[88:91], v[4:5], off
	global_load_dwordx4 v[92:95], v[8:9], off
	v_add_co_u32_e32 v4, vcc, s37, v14
	v_or_b32_e32 v12, v12, v96
	s_nop 0
	v_addc_co_u32_e32 v5, vcc, 0, v15, vcc
	global_load_dwordx4 v[80:83], v[6:7], off
	global_load_dwordx4 v[84:87], v[4:5], off
	v_and_b32_e32 v4, 31, v1
	v_lshrrev_b32_e32 v5, 1, v1
	v_and_b32_e32 v1, 0x5f, v1
	v_and_or_b32 v4, v5, s47, v4
	v_and_b32_e32 v5, 16, v5
	v_mul_u32_u24_e32 v1, 0x90, v1
	v_add3_u32 v117, 16, v1, v5
	v_ashrrev_i32_e32 v1, 31, v0
	v_mul_lo_u32 v4, v4, s46
	v_cmp_gt_i64_e32 vcc, s[28:29], v[0:1]
	v_add3_u32 v118, 16, v4, v5
	v_mul_lo_u32 v6, v16, s46
	v_cndmask_b32_e32 v5, 0, v1, vcc
	v_cndmask_b32_e32 v4, v111, v0, vcc
	v_cmp_gt_i64_e32 vcc, s[30:31], v[0:1]
	v_add3_u32 v99, 16, v6, v96
	v_lshlrev_b64 v[4:5], 11, v[4:5]
	v_cndmask_b32_e32 v3, 0, v1, vcc
	v_cndmask_b32_e32 v2, v112, v0, vcc
	v_cmp_gt_i64_e32 vcc, s[34:35], v[0:1]
	v_lshlrev_b64 v[2:3], 11, v[2:3]
	v_or_b32_e32 v4, v4, v96
	v_cndmask_b32_e32 v1, 0, v1, vcc
	v_cndmask_b32_e32 v0, v113, v0, vcc
	v_lshlrev_b64 v[0:1], 11, v[0:1]
	v_or_b32_e32 v0, v0, v96
	v_or_b32_e32 v2, v2, v96
	v_lshl_add_u64 v[106:107], s[26:27], 0, v[0:1]
	v_mov_b32_e32 v0, 0
	v_lshl_add_u64 v[102:103], s[22:23], 0, v[4:5]
	v_lshl_add_u64 v[104:105], s[24:25], 0, v[2:3]
	v_lshl_add_u64 v[108:109], s[48:49], 0, v[12:13]
	s_mov_b64 s[6:7], 0
	v_mov_b32_e32 v1, v0
	v_mov_b32_e32 v2, v0
	v_lshl_add_u64 v[226:227], v[100:101], 0, s[6:7]
	v_lshl_add_u64 v[228:229], v[102:103], 0, s[6:7]
	v_lshl_add_u64 v[230:231], v[104:105], 0, s[6:7]
	v_lshl_add_u64 v[238:239], v[106:107], 0, s[6:7]
	v_lshl_add_u64 v[248:249], v[108:109], 0, s[6:7]
	global_load_dwordx4 v[222:225], v[226:227], off
	s_nop 0
	global_load_dwordx4 v[226:229], v[228:229], off
	s_nop 0
	global_load_dwordx4 v[230:233], v[230:231], off
	s_nop 0
	global_load_dwordx4 v[234:237], v[238:239], off
	v_add_co_u32_e32 v238, vcc, 0x2010000, v248
	s_nop 1
	v_addc_co_u32_e32 v239, vcc, 0, v249, vcc
	v_add_co_u32_e32 v242, vcc, 0x2020000, v248
	s_nop 1
	v_addc_co_u32_e32 v243, vcc, 0, v249, vcc
	v_add_co_u32_e32 v250, vcc, 0x2030000, v248
	global_load_dwordx4 v[238:241], v[238:239], off offset:128
	s_nop 0
	global_load_dwordx4 v[242:245], v[242:243], off offset:128
	v_addc_co_u32_e32 v251, vcc, 0, v249, vcc
	v_add_co_u32_e32 v252, vcc, 0x2040000, v248
	s_nop 1
	v_addc_co_u32_e32 v253, vcc, 0, v249, vcc
	global_load_dwordx4 v[248:251], v[250:251], off offset:128
	s_nop 0
	global_load_dwordx4 v[252:255], v[252:253], off offset:128
	s_waitcnt vmcnt(13)
	ds_write_b128 v99, v[68:71]
	s_waitcnt vmcnt(12)
	ds_write_b128 v99, v[76:79] offset:36864
	s_waitcnt vmcnt(11)
	ds_write_b128 v99, v[88:91] offset:46080
	s_waitcnt vmcnt(10)
	ds_write_b128 v99, v[92:95] offset:50688
	ds_write_b128 v99, v[64:67] offset:4608
	ds_write_b128 v99, v[72:75] offset:9216
	s_waitcnt vmcnt(9)
	ds_write_b128 v99, v[80:83] offset:13824
	s_waitcnt vmcnt(8)
	ds_write_b128 v99, v[84:87] offset:41472
	s_waitcnt lgkmcnt(0)
	s_barrier
	v_mov_b32_e32 v3, v0
	v_mov_b32_e32 v4, v0
	v_mov_b32_e32 v5, v0
	v_mov_b32_e32 v6, v0
	v_mov_b32_e32 v7, v0
	v_mov_b32_e32 v8, v0
	v_mov_b32_e32 v9, v0
	v_mov_b32_e32 v10, v0
	v_mov_b32_e32 v11, v0
	v_mov_b32_e32 v12, v0
	v_mov_b32_e32 v13, v0
	v_mov_b32_e32 v14, v0
	v_mov_b32_e32 v15, v0
	v_mov_b32_e32 v16, v0
	v_mov_b32_e32 v17, v0
	v_mov_b32_e32 v18, v0
	v_mov_b32_e32 v19, v0
	v_mov_b32_e32 v20, v0
	v_mov_b32_e32 v21, v0
	v_mov_b32_e32 v22, v0
	v_mov_b32_e32 v23, v0
	v_mov_b32_e32 v24, v0
	v_mov_b32_e32 v25, v0
	v_mov_b32_e32 v26, v0
	v_mov_b32_e32 v27, v0
	v_mov_b32_e32 v28, v0
	v_mov_b32_e32 v29, v0
	v_mov_b32_e32 v30, v0
	v_mov_b32_e32 v31, v0
	v_mov_b32_e32 v32, v0
	v_mov_b32_e32 v33, v0
	v_mov_b32_e32 v34, v0
	v_mov_b32_e32 v35, v0
	v_mov_b32_e32 v36, v0
	v_mov_b32_e32 v37, v0
	v_mov_b32_e32 v38, v0
	v_mov_b32_e32 v39, v0
	v_mov_b32_e32 v40, v0
	v_mov_b32_e32 v41, v0
	v_mov_b32_e32 v42, v0
	v_mov_b32_e32 v43, v0
	v_mov_b32_e32 v44, v0
	v_mov_b32_e32 v45, v0
	v_mov_b32_e32 v46, v0
	v_mov_b32_e32 v47, v0
	v_mov_b32_e32 v48, v0
	v_mov_b32_e32 v49, v0
	v_mov_b32_e32 v50, v0
	v_mov_b32_e32 v51, v0
	v_mov_b32_e32 v52, v0
	v_mov_b32_e32 v53, v0
	v_mov_b32_e32 v54, v0
	v_mov_b32_e32 v55, v0
	v_mov_b32_e32 v56, v0
	v_mov_b32_e32 v57, v0
	v_mov_b32_e32 v58, v0
	v_mov_b32_e32 v59, v0
	v_mov_b32_e32 v60, v0
	v_mov_b32_e32 v61, v0
	v_mov_b32_e32 v62, v0
	v_mov_b32_e32 v63, v0
	s_branch .LBB0_97

; __device__ __forceinline__ int ltid() { int t = threadIdx.x; asm volatile("" : "+v"(t)); return t; }
; __device__ __forceinline__ void stage_acc(f32x16 (&acc)[2][2], float* sC) {
;   const int tid__ = ltid(); const int lane = tid__ & 63, wave = tid__ >> 6;
;   const int wm = wave >> 1, wn = wave & 1, l31 = lane & 31, hf = lane >> 5;
;   float* base = sC + (wm * 64 + 4 * hf) * 132 + wn * 64 + l31;
; #pragma unroll
;   for (int mi = 0; mi < 2; ++mi)
; #pragma unroll
;     for (int ni = 0; ni < 2; ++ni)
; #pragma unroll
;       for (int r = 0; r < 16; ++r) base[(mi * 32 + 8 * (r >> 2) + (r & 3)) * 132 + ni * 32] = acc[mi][ni][r];
;   __syncthreads();
; __device__ __forceinline__ void phase1(const Params& p, unsigned char* smem) {
;     ...
;       epilogue_rows(acc, m0, n0, smem, [&](int m, int n, float4 a, float4 b) {
;         if (m < NTOK && n < 8208) {
;           int isg = n >= 8200;
;           int bb = m / LTOK, pos = m - bb * LTOK;
.LBB0_101:
	v_cmp_eq_u32_e32 vcc, 0, v218
	s_and_saveexec_b64 s[84:85], vcc
	s_cbranch_execz .Ltq1_b_skip
	s_waitcnt vmcnt(0)
	ds_write_b32 v97, v246
.Ltq1_b_skip:
	s_or_b64 exec, exec, s[84:85]
	s_cmp_gt_i32 s68, 7
	s_mov_b64 s[6:7], -1
	s_cbranch_scc0 .LBB0_237
	s_cmp_gt_u32 s68, 15
	s_cbranch_scc0 .LBB0_228
	s_and_b64 vcc, exec, s[4:5]
	s_cbranch_vccz .LBB0_219
	s_cmp_gt_u32 s68, 47
	s_mov_b64 s[4:5], -1
	s_cbranch_scc0 .LBB0_208
	s_waitcnt vmcnt(6)
	v_mov_b32_e32 v64, v218
	s_waitcnt vmcnt(5)
	v_mov_b32_e32 v73, v218
	v_and_b32_e32 v65, 64, v64
	v_and_b32_e32 v66, 31, v64
	v_lshrrev_b32_e32 v67, 1, v64
	v_lshrrev_b32_e32 v64, 3, v64
	v_and_b32_e32 v64, 4, v64
	v_and_or_b32 v64, v67, s47, v64
	v_mul_lo_u32 v64, v64, s52
	v_add_u32_e32 v64, 16, v64
	v_lshlrev_b32_e32 v65, 2, v65
	v_lshlrev_b32_e32 v66, 2, v66
	v_add3_u32 v64, v64, v65, v66
	v_add_u32_e32 v65, 0x400, v64
	ds_write2_b32 v64, v48, v32 offset1:32
	ds_write2_b32 v64, v49, v33 offset0:132 offset1:164
	ds_write2_b32 v65, v50, v34 offset0:8 offset1:40
	ds_write2_b32 v65, v51, v35 offset0:140 offset1:172
	v_add_u32_e32 v65, 0x1000, v64
	ds_write2_b32 v65, v52, v36 offset0:32 offset1:64
	ds_write2_b32 v65, v53, v37 offset0:164 offset1:196
	v_add_u32_e32 v65, 0x1400, v64
	ds_write2_b32 v65, v54, v38 offset0:40 offset1:72
	ds_write2_b32 v65, v55, v39 offset0:172 offset1:204
	v_add_u32_e32 v65, 0x2000, v64
	ds_write2_b32 v65, v56, v40 offset0:64 offset1:96
	ds_write2_b32 v65, v57, v41 offset0:196 offset1:228
	v_add_u32_e32 v65, 0x2400, v64
	ds_write2_b32 v65, v58, v42 offset0:72 offset1:104
	ds_write2_b32 v65, v59, v43 offset0:204 offset1:236
	v_add_u32_e32 v65, 0x3000, v64
	ds_write2_b32 v65, v60, v44 offset0:96 offset1:128
	v_add_u32_e32 v65, 0x3200, v64
	ds_write2_b32 v65, v61, v45 offset0:100 offset1:132
	v_add_u32_e32 v65, 0x3400, v64
	ds_write2_b32 v65, v62, v46 offset0:104 offset1:136
	v_add_u32_e32 v65, 0x3600, v64
	ds_write2_b32 v65, v63, v47 offset0:108 offset1:140
	v_add_u32_e32 v65, 0x4000, v64
	ds_write2_b32 v65, v16, v0 offset0:128 offset1:160
	v_add_u32_e32 v65, 0x4400, v64
	ds_write2_b32 v65, v17, v1 offset0:4 offset1:36
	ds_write2_b32 v65, v18, v2 offset0:136 offset1:168
	v_add_u32_e32 v65, 0x4800, v64
	ds_write2_b32 v65, v19, v3 offset0:12 offset1:44
	v_add_u32_e32 v65, 0x5000, v64
	ds_write2_b32 v65, v20, v4 offset0:160 offset1:192
	v_add_u32_e32 v65, 0x5400, v64
	ds_write2_b32 v65, v21, v5 offset0:36 offset1:68
	ds_write2_b32 v65, v22, v6 offset0:168 offset1:200
	v_add_u32_e32 v65, 0x5800, v64
	ds_write2_b32 v65, v23, v7 offset0:44 offset1:76
	v_add_u32_e32 v65, 0x6000, v64
	ds_write2_b32 v65, v24, v8 offset0:192 offset1:224
	v_add_u32_e32 v65, 0x6400, v64
	ds_write2_b32 v65, v25, v9 offset0:68 offset1:100
	ds_write2_b32 v65, v26, v10 offset0:200 offset1:232
	v_add_u32_e32 v65, 0x6800, v64
	ds_write2_b32 v65, v27, v11 offset0:76 offset1:108
	v_add_u32_e32 v65, 0x7200, v64
	ds_write2_b32 v65, v28, v12 offset0:96 offset1:128
	v_add_u32_e32 v65, 0x7400, v64
	ds_write2_b32 v65, v29, v13 offset0:100 offset1:132
	v_add_u32_e32 v65, 0x7600, v64
	v_add_u32_e32 v64, 0x7800, v64
	ds_write2_b32 v65, v30, v14 offset0:104 offset1:136
	ds_write2_b32 v64, v31, v15 offset0:108 offset1:140
	s_waitcnt lgkmcnt(0)
	s_barrier
	s_mov_b32 s72, 0
	v_lshlrev_b32_e32 v64, 3, v73
	v_and_b32_e32 v64, 0x78, v64
	v_lshl_add_u32 v72, v64, 2, 16
	v_add_u32_e32 v64, s71, v64
	v_cmp_gt_i32_e64 s[6:7], s53, v64
	v_cmp_gt_i32_e64 s[4:5], s54, v64
	s_branch .LBB0_109
